# P3 tile rebalance across the panel cluster + peeled K-loop (no acc zeroing) + saddr DMA + barrier/prio edits
# baseline (speedup 1.0000x reference)
.LBB0_459:
	s_mov_b32 s40, s38
	s_add_i32 s38, s38, 1
	s_cmp_lt_u32 s38, s7
	s_mov_b32 s35, s39
	s_cselect_b64 s[42:43], -1, 0
	s_add_i32 s39, s38, s6
	s_sub_i32 s98, s39, 11
	s_cmp_lt_u32 s98, 3
	s_cselect_b32 s99, 7, 0
	s_sub_i32 s98, s39, 18
	s_cmp_lt_u32 s98, 3
	s_cselect_b32 s98, 0xfffffff9, 0
	s_add_i32 s99, s99, s98
	s_cmp_eq_u32 s39, 6
	s_cselect_b32 s98, 11, 0
	s_add_i32 s99, s99, s98
	s_cmp_eq_u32 s39, 17
	s_cselect_b32 s98, 0xfffffff5, 0
	s_add_i32 s99, s99, s98
	s_add_i32 s39, s39, s99
	s_and_b64 s[44:45], s[42:43], exec
	s_cselect_b32 s46, s58, s58
	s_cselect_b32 s44, s39, s35
	s_ashr_i32 s47, s46, 31
	s_lshl_b64 s[46:47], s[46:47], 19
	s_mov_b64 s[4:5], s[82:83]
	s_add_u32 s82, s60, s46
	s_addc_u32 s83, s33, s47
	s_and_b64 s[46:47], s[42:43], exec
	s_cselect_b32 s35, s83, s5
	s_cselect_b32 s41, s82, s4
	s_ashr_i32 s45, s44, 31
	s_lshl_b64 s[44:45], s[44:45], 19
	v_readlane_b32 s12, v253, 61
	s_mov_b64 s[8:9], s[62:63]
	v_readlane_b32 s13, v253, 62
	s_add_u32 s62, s12, s44
	s_addc_u32 s63, s13, s45
	s_and_b64 s[42:43], s[42:43], exec
	s_cselect_b32 s42, s63, s9
	s_cselect_b32 s43, s62, s8
	s_add_u32 s44, s8, 0x10000
	s_addc_u32 s45, s9, 0
	s_mov_b32 s46, -2
	v_add_u32_e32 v134, s95, v1
	ds_read_b128 v[130:133], v134
	ds_read_b128 v[136:139], v134 offset:1024
	ds_read_b128 v[140:143], v134 offset:2048
	ds_read_b128 v[144:147], v134 offset:3072
	v_add_u32_e32 v134, s93, v1
	ds_read_b128 v[170:173], v134
	ds_read_b128 v[200:203], v134 offset:1024
	ds_read_b128 v[204:207], v134 offset:2048
	ds_read_b128 v[208:211], v134 offset:3072
	s_add_u32 s8, s4, 0x10000
	s_addc_u32 s9, s5, 0
	s_cmp_eq_u32 s46, 12
	s_cselect_b32 s84, s41, s8
	s_cselect_b32 s85, s35, s9
	s_cselect_b32 s64, s43, s44
	s_cselect_b32 s65, s42, s45
	s_add_u32 s56, s84, 0x8000
	s_addc_u32 s57, s85, 0
	s_add_i32 m0, s69, 0xc000
	ds_read_b128 v[212:215], v194
	ds_read_b128 v[216:219], v194 offset:1024
	ds_read_b128 v[220:223], v194 offset:2048
	ds_read_b128 v[224:227], v194 offset:3072
	ds_read_b128 v[228:231], v194 offset:4096
	ds_read_b128 v[232:235], v194 offset:5120
	ds_read_b128 v[236:239], v194 offset:6144
	ds_read_b128 v[240:243], v194 offset:7168
	global_load_lds_dwordx4 v166, s[4:5] sc1
	s_add_i32 m0, s69, 0xe000
	s_nop 0
	global_load_lds_dwordx4 v168, s[4:5] sc1
	s_waitcnt vmcnt(8)
	s_waitcnt lgkmcnt(0)
	s_setprio 1
	s_barrier
	v_mfma_f32_16x16x32_bf16 v[122:125], v[130:133], v[212:215], 0
	v_mfma_f32_16x16x32_bf16 v[126:129], v[140:143], v[212:215], 0
	v_mfma_f32_16x16x32_bf16 v[106:109], v[130:133], v[220:223], 0
	v_mfma_f32_16x16x32_bf16 v[110:113], v[140:143], v[220:223], 0
	v_mfma_f32_16x16x32_bf16 v[90:93], v[130:133], v[228:231], 0
	v_mfma_f32_16x16x32_bf16 v[94:97], v[140:143], v[228:231], 0
	v_mfma_f32_16x16x32_bf16 v[74:77], v[130:133], v[236:239], 0
	v_mfma_f32_16x16x32_bf16 v[78:81], v[140:143], v[236:239], 0
	v_mfma_f32_16x16x32_bf16 v[122:125], v[136:139], v[216:219], v[122:125]
	v_mfma_f32_16x16x32_bf16 v[126:129], v[144:147], v[216:219], v[126:129]
	v_mfma_f32_16x16x32_bf16 v[106:109], v[136:139], v[224:227], v[106:109]
	v_mfma_f32_16x16x32_bf16 v[110:113], v[144:147], v[224:227], v[110:113]
	v_mfma_f32_16x16x32_bf16 v[90:93], v[136:139], v[232:235], v[90:93]
	v_mfma_f32_16x16x32_bf16 v[94:97], v[144:147], v[232:235], v[94:97]
	v_mfma_f32_16x16x32_bf16 v[74:77], v[136:139], v[240:243], v[74:77]
	v_mfma_f32_16x16x32_bf16 v[78:81], v[144:147], v[240:243], v[78:81]
	v_mfma_f32_16x16x32_bf16 v[114:117], v[170:173], v[212:215], 0
	v_mfma_f32_16x16x32_bf16 v[118:121], v[204:207], v[212:215], 0
	v_mfma_f32_16x16x32_bf16 v[98:101], v[170:173], v[220:223], 0
	v_mfma_f32_16x16x32_bf16 v[102:105], v[204:207], v[220:223], 0
	v_mfma_f32_16x16x32_bf16 v[82:85], v[170:173], v[228:231], 0
	v_mfma_f32_16x16x32_bf16 v[86:89], v[204:207], v[228:231], 0
	v_mfma_f32_16x16x32_bf16 v[66:69], v[170:173], v[236:239], 0
	v_mfma_f32_16x16x32_bf16 v[70:73], v[204:207], v[236:239], 0
	v_mfma_f32_16x16x32_bf16 v[114:117], v[200:203], v[216:219], v[114:117]
	v_mfma_f32_16x16x32_bf16 v[118:121], v[208:211], v[216:219], v[118:121]
	v_mfma_f32_16x16x32_bf16 v[98:101], v[200:203], v[224:227], v[98:101]
	v_mfma_f32_16x16x32_bf16 v[102:105], v[208:211], v[224:227], v[102:105]
	v_mfma_f32_16x16x32_bf16 v[82:85], v[200:203], v[232:235], v[82:85]
	v_mfma_f32_16x16x32_bf16 v[86:89], v[208:211], v[232:235], v[86:89]
	s_setprio 2
	s_barrier
	v_mfma_f32_16x16x32_bf16 v[66:69], v[200:203], v[240:243], v[66:69]
	v_mfma_f32_16x16x32_bf16 v[70:73], v[208:211], v[240:243], v[70:73]
	s_setprio 0
	s_add_i32 s4, s95, s61
	s_mov_b32 m0, s4
	ds_read_b128 v[212:215], v194 offset:16384
	ds_read_b128 v[216:219], v194 offset:17408
	ds_read_b128 v[220:223], v194 offset:18432
	ds_read_b128 v[224:227], v194 offset:19456
	ds_read_b128 v[228:231], v194 offset:20480
	ds_read_b128 v[232:235], v194 offset:21504
	ds_read_b128 v[236:239], v194 offset:22528
	ds_read_b128 v[240:243], v194 offset:23552
	global_load_lds_dwordx4 v152, s[64:65] sc1
	s_add_i32 m0, s4, 0x2000
	s_add_u32 s4, s64, 0x4000
	s_addc_u32 s5, s65, 0
	s_add_i32 s47, s93, s61
	global_load_lds_dwordx4 v154, s[64:65] sc1
	s_mov_b32 m0, s47
	s_nop 0
	global_load_lds_dwordx4 v152, s[4:5] sc1
	s_add_i32 m0, s47, 0x2000
	s_nop 0
	global_load_lds_dwordx4 v154, s[4:5] sc1
	s_mov_b32 m0, s69
	s_nop 0
	global_load_lds_dwordx4 v150, s[84:85] sc1
	s_mov_b32 m0, s77
	s_nop 0
	global_load_lds_dwordx4 v148, s[84:85] sc1
	s_waitcnt vmcnt(8)
	s_waitcnt lgkmcnt(0)
	s_setprio 1
	s_barrier
	v_mfma_f32_16x16x32_bf16 v[58:61], v[130:133], v[212:215], 0
	v_mfma_f32_16x16x32_bf16 v[62:65], v[140:143], v[212:215], 0
	v_mfma_f32_16x16x32_bf16 v[42:45], v[130:133], v[220:223], 0
	v_mfma_f32_16x16x32_bf16 v[46:49], v[140:143], v[220:223], 0
	v_mfma_f32_16x16x32_bf16 v[26:29], v[130:133], v[228:231], 0
	v_mfma_f32_16x16x32_bf16 v[30:33], v[140:143], v[228:231], 0
	v_mfma_f32_16x16x32_bf16 v[10:13], v[130:133], v[236:239], 0
	v_mfma_f32_16x16x32_bf16 v[14:17], v[140:143], v[236:239], 0
	v_mfma_f32_16x16x32_bf16 v[58:61], v[136:139], v[216:219], v[58:61]
	v_mfma_f32_16x16x32_bf16 v[62:65], v[144:147], v[216:219], v[62:65]
	v_mfma_f32_16x16x32_bf16 v[42:45], v[136:139], v[224:227], v[42:45]
	v_mfma_f32_16x16x32_bf16 v[46:49], v[144:147], v[224:227], v[46:49]
	v_mfma_f32_16x16x32_bf16 v[26:29], v[136:139], v[232:235], v[26:29]
	v_mfma_f32_16x16x32_bf16 v[30:33], v[144:147], v[232:235], v[30:33]
	v_mfma_f32_16x16x32_bf16 v[10:13], v[136:139], v[240:243], v[10:13]
	v_mfma_f32_16x16x32_bf16 v[14:17], v[144:147], v[240:243], v[14:17]
	v_mfma_f32_16x16x32_bf16 v[50:53], v[170:173], v[212:215], 0
	v_mfma_f32_16x16x32_bf16 v[54:57], v[204:207], v[212:215], 0
	v_mfma_f32_16x16x32_bf16 v[34:37], v[170:173], v[220:223], 0
	v_mfma_f32_16x16x32_bf16 v[38:41], v[204:207], v[220:223], 0
	v_mfma_f32_16x16x32_bf16 v[18:21], v[170:173], v[228:231], 0
	v_mfma_f32_16x16x32_bf16 v[22:25], v[204:207], v[228:231], 0
	v_mfma_f32_16x16x32_bf16 v[2:5], v[170:173], v[236:239], 0
	v_mfma_f32_16x16x32_bf16 v[6:9], v[204:207], v[236:239], 0
	v_mfma_f32_16x16x32_bf16 v[50:53], v[200:203], v[216:219], v[50:53]
	v_mfma_f32_16x16x32_bf16 v[54:57], v[208:211], v[216:219], v[54:57]
	v_mfma_f32_16x16x32_bf16 v[34:37], v[200:203], v[224:227], v[34:37]
	v_mfma_f32_16x16x32_bf16 v[38:41], v[208:211], v[224:227], v[38:41]
	v_mfma_f32_16x16x32_bf16 v[18:21], v[200:203], v[232:235], v[18:21]
	v_mfma_f32_16x16x32_bf16 v[22:25], v[208:211], v[232:235], v[22:25]
	s_setprio 2
	s_barrier
	v_mfma_f32_16x16x32_bf16 v[2:5], v[200:203], v[240:243], v[2:5]
	v_mfma_f32_16x16x32_bf16 v[6:9], v[208:211], v[240:243], v[6:9]
	s_setprio 0
	v_add_u32_e32 v134, s36, v1
	ds_read_b128 v[130:133], v134
	ds_read_b128 v[136:139], v134 offset:1024
	ds_read_b128 v[140:143], v134 offset:2048
	ds_read_b128 v[144:147], v134 offset:3072
	v_add_u32_e32 v134, s37, v1
	ds_read_b128 v[170:173], v134
	ds_read_b128 v[200:203], v134 offset:1024
	ds_read_b128 v[204:207], v134 offset:2048
	ds_read_b128 v[208:211], v134 offset:3072
	s_add_u32 s4, s84, 0x4000
	s_addc_u32 s5, s85, 0
	s_mov_b32 m0, s86
	ds_read_b128 v[212:215], v194 offset:32768
	ds_read_b128 v[216:219], v194 offset:33792
	ds_read_b128 v[220:223], v194 offset:34816
	ds_read_b128 v[224:227], v194 offset:35840
	ds_read_b128 v[228:231], v194 offset:36864
	ds_read_b128 v[232:235], v194 offset:37888
	ds_read_b128 v[236:239], v194 offset:38912
	ds_read_b128 v[240:243], v194 offset:39936
	global_load_lds_dwordx4 v150, s[4:5] sc1
	s_mov_b32 m0, s87
	s_nop 0
	global_load_lds_dwordx4 v148, s[4:5] sc1
	s_waitcnt vmcnt(8)
	s_waitcnt lgkmcnt(0)
	s_setprio 1
	s_barrier
	v_mfma_f32_16x16x32_bf16 v[122:125], v[130:133], v[212:215], v[122:125]
	v_mfma_f32_16x16x32_bf16 v[126:129], v[140:143], v[212:215], v[126:129]
	v_mfma_f32_16x16x32_bf16 v[106:109], v[130:133], v[220:223], v[106:109]
	v_mfma_f32_16x16x32_bf16 v[110:113], v[140:143], v[220:223], v[110:113]
	v_mfma_f32_16x16x32_bf16 v[90:93], v[130:133], v[228:231], v[90:93]
	v_mfma_f32_16x16x32_bf16 v[94:97], v[140:143], v[228:231], v[94:97]
	v_mfma_f32_16x16x32_bf16 v[74:77], v[130:133], v[236:239], v[74:77]
	v_mfma_f32_16x16x32_bf16 v[78:81], v[140:143], v[236:239], v[78:81]
	v_mfma_f32_16x16x32_bf16 v[122:125], v[136:139], v[216:219], v[122:125]
	v_mfma_f32_16x16x32_bf16 v[126:129], v[144:147], v[216:219], v[126:129]
	v_mfma_f32_16x16x32_bf16 v[106:109], v[136:139], v[224:227], v[106:109]
	v_mfma_f32_16x16x32_bf16 v[110:113], v[144:147], v[224:227], v[110:113]
	v_mfma_f32_16x16x32_bf16 v[90:93], v[136:139], v[232:235], v[90:93]
	v_mfma_f32_16x16x32_bf16 v[94:97], v[144:147], v[232:235], v[94:97]
	v_mfma_f32_16x16x32_bf16 v[74:77], v[136:139], v[240:243], v[74:77]
	v_mfma_f32_16x16x32_bf16 v[78:81], v[144:147], v[240:243], v[78:81]
	v_mfma_f32_16x16x32_bf16 v[114:117], v[170:173], v[212:215], v[114:117]
	v_mfma_f32_16x16x32_bf16 v[118:121], v[204:207], v[212:215], v[118:121]
	v_mfma_f32_16x16x32_bf16 v[98:101], v[170:173], v[220:223], v[98:101]
	v_mfma_f32_16x16x32_bf16 v[102:105], v[204:207], v[220:223], v[102:105]
	v_mfma_f32_16x16x32_bf16 v[82:85], v[170:173], v[228:231], v[82:85]
	v_mfma_f32_16x16x32_bf16 v[86:89], v[204:207], v[228:231], v[86:89]
	v_mfma_f32_16x16x32_bf16 v[66:69], v[170:173], v[236:239], v[66:69]
	v_mfma_f32_16x16x32_bf16 v[70:73], v[204:207], v[236:239], v[70:73]
	v_mfma_f32_16x16x32_bf16 v[114:117], v[200:203], v[216:219], v[114:117]
	v_mfma_f32_16x16x32_bf16 v[118:121], v[208:211], v[216:219], v[118:121]
	v_mfma_f32_16x16x32_bf16 v[98:101], v[200:203], v[224:227], v[98:101]
	v_mfma_f32_16x16x32_bf16 v[102:105], v[208:211], v[224:227], v[102:105]
	v_mfma_f32_16x16x32_bf16 v[82:85], v[200:203], v[232:235], v[82:85]
	v_mfma_f32_16x16x32_bf16 v[86:89], v[208:211], v[232:235], v[86:89]
	s_setprio 2
	s_barrier
	v_mfma_f32_16x16x32_bf16 v[66:69], v[200:203], v[240:243], v[66:69]
	v_mfma_f32_16x16x32_bf16 v[70:73], v[208:211], v[240:243], v[70:73]
	s_setprio 0
	s_add_u32 s4, s64, 0x8000
	s_addc_u32 s5, s65, 0
	s_add_i32 s47, s36, s61
	s_mov_b32 m0, s47
	ds_read_b128 v[212:215], v194 offset:49152
	ds_read_b128 v[216:219], v194 offset:50176
	ds_read_b128 v[220:223], v194 offset:51200
	ds_read_b128 v[224:227], v194 offset:52224
	ds_read_b128 v[228:231], v194 offset:53248
	ds_read_b128 v[232:235], v194 offset:54272
	ds_read_b128 v[236:239], v194 offset:55296
	ds_read_b128 v[240:243], v194 offset:56320
	global_load_lds_dwordx4 v152, s[4:5] sc1
	s_add_i32 m0, s47, 0x2000
	s_nop 0
	global_load_lds_dwordx4 v154, s[4:5] sc1
	s_add_u32 s4, s64, 0xc000
	s_addc_u32 s5, s65, 0
	s_add_i32 s47, s37, s61
	s_mov_b32 m0, s47
	s_nop 0
	global_load_lds_dwordx4 v152, s[4:5] sc1
	s_add_i32 m0, s47, 0x2000
	s_nop 0
	global_load_lds_dwordx4 v154, s[4:5] sc1
	s_mov_b32 m0, s91
	s_nop 0
	global_load_lds_dwordx4 v150, s[56:57] sc1
	s_mov_b32 m0, s92
	s_nop 0
	global_load_lds_dwordx4 v148, s[56:57] sc1
	s_waitcnt vmcnt(8)
	s_waitcnt lgkmcnt(0)
	s_setprio 1
	s_barrier
	v_mfma_f32_16x16x32_bf16 v[58:61], v[130:133], v[212:215], v[58:61]
	v_mfma_f32_16x16x32_bf16 v[62:65], v[140:143], v[212:215], v[62:65]
	v_mfma_f32_16x16x32_bf16 v[42:45], v[130:133], v[220:223], v[42:45]
	v_mfma_f32_16x16x32_bf16 v[46:49], v[140:143], v[220:223], v[46:49]
	v_mfma_f32_16x16x32_bf16 v[26:29], v[130:133], v[228:231], v[26:29]
	v_mfma_f32_16x16x32_bf16 v[30:33], v[140:143], v[228:231], v[30:33]
	v_mfma_f32_16x16x32_bf16 v[10:13], v[130:133], v[236:239], v[10:13]
	v_mfma_f32_16x16x32_bf16 v[14:17], v[140:143], v[236:239], v[14:17]
	v_mfma_f32_16x16x32_bf16 v[58:61], v[136:139], v[216:219], v[58:61]
	v_mfma_f32_16x16x32_bf16 v[62:65], v[144:147], v[216:219], v[62:65]
	v_mfma_f32_16x16x32_bf16 v[42:45], v[136:139], v[224:227], v[42:45]
	v_mfma_f32_16x16x32_bf16 v[46:49], v[144:147], v[224:227], v[46:49]
	v_mfma_f32_16x16x32_bf16 v[26:29], v[136:139], v[232:235], v[26:29]
	v_mfma_f32_16x16x32_bf16 v[30:33], v[144:147], v[232:235], v[30:33]
	v_mfma_f32_16x16x32_bf16 v[10:13], v[136:139], v[240:243], v[10:13]
	v_mfma_f32_16x16x32_bf16 v[14:17], v[144:147], v[240:243], v[14:17]
	v_mfma_f32_16x16x32_bf16 v[50:53], v[170:173], v[212:215], v[50:53]
	v_mfma_f32_16x16x32_bf16 v[54:57], v[204:207], v[212:215], v[54:57]
	v_mfma_f32_16x16x32_bf16 v[34:37], v[170:173], v[220:223], v[34:37]
	v_mfma_f32_16x16x32_bf16 v[38:41], v[204:207], v[220:223], v[38:41]
	v_mfma_f32_16x16x32_bf16 v[18:21], v[170:173], v[228:231], v[18:21]
	v_mfma_f32_16x16x32_bf16 v[22:25], v[204:207], v[228:231], v[22:25]
	v_mfma_f32_16x16x32_bf16 v[2:5], v[170:173], v[236:239], v[2:5]
	v_mfma_f32_16x16x32_bf16 v[6:9], v[204:207], v[236:239], v[6:9]
	v_mfma_f32_16x16x32_bf16 v[50:53], v[200:203], v[216:219], v[50:53]
	v_mfma_f32_16x16x32_bf16 v[54:57], v[208:211], v[216:219], v[54:57]
	v_mfma_f32_16x16x32_bf16 v[34:37], v[200:203], v[224:227], v[34:37]
	v_mfma_f32_16x16x32_bf16 v[38:41], v[208:211], v[224:227], v[38:41]
	v_mfma_f32_16x16x32_bf16 v[18:21], v[200:203], v[232:235], v[18:21]
	v_mfma_f32_16x16x32_bf16 v[22:25], v[208:211], v[232:235], v[22:25]
	s_setprio 2
	s_barrier
	v_mfma_f32_16x16x32_bf16 v[2:5], v[200:203], v[240:243], v[2:5]
	v_mfma_f32_16x16x32_bf16 v[6:9], v[208:211], v[240:243], v[6:9]
	s_setprio 0
	s_add_i32 s46, s46, 2
	s_add_u32 s44, s44, 0x10000
	s_addc_u32 s45, s45, 0
	s_cmp_gt_u32 s46, 13
	s_mov_b64 s[4:5], s[8:9]

.LBB0_463:
	s_add_i32 s46, s40, s6
	s_sub_i32 s98, s46, 11
	s_cmp_lt_u32 s98, 3
	s_cselect_b32 s99, 7, 0
	s_sub_i32 s98, s46, 18
	s_cmp_lt_u32 s98, 3
	s_cselect_b32 s98, 0xfffffff9, 0
	s_add_i32 s99, s99, s98
	s_cmp_eq_u32 s46, 6
	s_cselect_b32 s98, 11, 0
	s_add_i32 s99, s99, s98
	s_cmp_eq_u32 s46, 17
	s_cselect_b32 s98, 0xfffffff5, 0
	s_add_i32 s99, s99, s98
	s_add_i32 s46, s46, s99
	s_sub_i32 s4, s46, 22
	s_cmp_gt_u32 s4, 0xffffffef
	s_mov_b64 s[4:5], -1
	s_cbranch_scc0 .LBB0_529
	s_cmp_gt_u32 s46, 13
	s_cselect_b64 s[8:9], -1, 0
	s_cmp_lt_u32 s46, 14
	s_cselect_b64 s[56:57], -1, 0
	s_lshl_b32 s4, s40, 10
	v_add_u32_e32 v196, s4, v176
	ds_read_b32 v134, v196
	s_mov_b64 s[4:5], -1
	s_and_b64 vcc, exec, s[8:9]
	s_waitcnt lgkmcnt(0)
	v_mul_f32_e32 v130, v134, v134
	v_mov_b32_e32 v131, v130
	v_mov_b32_e32 v132, v130
	s_cbranch_vccnz .LBB0_466
	v_mov_b32_e32 v133, v130
	v_mov_b64_e32 v[138:139], v[132:133]
	v_mov_b64_e32 v[142:143], v[116:117]
	s_mov_b64 s[4:5], 0
	v_mov_b64_e32 v[136:137], v[130:131]
	v_mov_b64_e32 v[140:141], v[114:115]

	.amdhsa_kernel _Z14fwd_megakernel6Params
		.amdhsa_group_segment_fixed_size 256
		.amdhsa_private_segment_fixed_size 0
		.amdhsa_kernarg_size 440
		.amdhsa_user_sgpr_count 2
		.amdhsa_user_sgpr_dispatch_ptr 0
		.amdhsa_user_sgpr_queue_ptr 0
		.amdhsa_user_sgpr_kernarg_segment_ptr 1
		.amdhsa_user_sgpr_dispatch_id 0
		.amdhsa_user_sgpr_kernarg_preload_length 0
		.amdhsa_user_sgpr_kernarg_preload_offset 0
		.amdhsa_user_sgpr_private_segment_size 0
		.amdhsa_uses_dynamic_stack 0
		.amdhsa_enable_private_segment 0
		.amdhsa_system_sgpr_workgroup_id_x 1
		.amdhsa_system_sgpr_workgroup_id_y 0
		.amdhsa_system_sgpr_workgroup_id_z 0
		.amdhsa_system_sgpr_workgroup_info 0
		.amdhsa_system_vgpr_workitem_id 2
		.amdhsa_next_free_vgpr 254
		.amdhsa_next_free_sgpr 102
		.amdhsa_accum_offset 256
		.amdhsa_reserve_vcc 1
		.amdhsa_float_round_mode_32 0
		.amdhsa_float_round_mode_16_64 0
		.amdhsa_float_denorm_mode_32 3
		.amdhsa_float_denorm_mode_16_64 3
		.amdhsa_dx10_clamp 1
		.amdhsa_ieee_mode 1
		.amdhsa_fp16_overflow 0
		.amdhsa_tg_split 0
		.amdhsa_exception_fp_ieee_invalid_op 0
		.amdhsa_exception_fp_denorm_src 0
		.amdhsa_exception_fp_ieee_div_zero 0
		.amdhsa_exception_fp_ieee_overflow 0
		.amdhsa_exception_fp_ieee_underflow 0
		.amdhsa_exception_fp_ieee_inexact 0
		.amdhsa_exception_int_div_zero 0
	.end_amdhsa_kernel

amdhsa.kernels:
  - .agpr_count:     0
    .args:
      - .offset:         0
        .size:           184
        .value_kind:     by_value
      - .offset:         184
        .size:           4
        .value_kind:     hidden_block_count_x
      - .offset:         188
        .size:           4
        .value_kind:     hidden_block_count_y
      - .offset:         192
        .size:           4
        .value_kind:     hidden_block_count_z
      - .offset:         196
        .size:           2
        .value_kind:     hidden_group_size_x
      - .offset:         198
        .size:           2
        .value_kind:     hidden_group_size_y
      - .offset:         200
        .size:           2
        .value_kind:     hidden_group_size_z
      - .offset:         202
        .size:           2
        .value_kind:     hidden_remainder_x
      - .offset:         204
        .size:           2
        .value_kind:     hidden_remainder_y
      - .offset:         206
        .size:           2
        .value_kind:     hidden_remainder_z
      - .offset:         224
        .size:           8
        .value_kind:     hidden_global_offset_x
      - .offset:         232
        .size:           8
        .value_kind:     hidden_global_offset_y
      - .offset:         240
        .size:           8
        .value_kind:     hidden_global_offset_z
      - .offset:         248
        .size:           2
        .value_kind:     hidden_grid_dims
      - .offset:         304
        .size:           4
        .value_kind:     hidden_dynamic_lds_size
    .group_segment_fixed_size: 256
    .kernarg_segment_align: 8
    .kernarg_segment_size: 440
    .language:       OpenCL C
    .language_version:
      - 2
      - 0
    .max_flat_workgroup_size: 512
    .name:           _Z14fwd_megakernel6Params
    .private_segment_fixed_size: 0
    .sgpr_count:     108
    .sgpr_spill_count: 143
    .symbol:         _Z14fwd_megakernel6Params.kd
    .uniform_work_group_size: 1
    .uses_dynamic_stack: false
    .vgpr_count:     254
    .vgpr_spill_count: 0
    .wavefront_size: 64
